# hgrn stage 2 fast path: one barrier per chunk (ping-pong LDS tiles), batched fragment reads, outputs stored from accumulator lanes, 4-deep counted prefetch
# baseline (speedup 1.0000x reference)
.LBB0_550:
	v_readlane_b32 s6, v250, 2
	s_nop 3
	s_cmp_lg_u32 s6, 0
	s_cbranch_scc0 .Ls2_orig
	s_lshr_b32 s7, s24, 4
	s_and_b32 s8, s24, 3
	s_lshr_b32 s9, s24, 2
	s_lshl_b32 s9, s9, 6
	s_mul_i32 s23, s7, 12
	s_add_u32 s26, s23, 8
	s_lshl_b32 s26, s26, 20
	s_lshl_b32 s27, s9, 14
	s_add_u32 s26, s26, s27
	s_add_u32 s10, s38, s26
	s_addc_u32 s11, s39, 0
	s_lshl_b32 s26, s7, 23
	s_lshl_b32 s30, s9, 15
	s_add_u32 s26, s26, s30
	s_add_u32 s12, s38, s26
	s_addc_u32 s13, s39, 0
	s_add_u32 s26, s23, 12
	s_lshl_b32 s26, s26, 20
	s_add_u32 s26, s26, s27
	s_add_u32 s14, s38, s26
	s_addc_u32 s15, s39, 0
	v_readlane_b32 s16, v248, 29
	v_readlane_b32 s17, v248, 30
	s_lshl_b32 s26, s9, 9
	s_nop 1
	s_add_u32 s16, s16, s26
	s_addc_u32 s17, s17, 0
	v_readlane_b32 s18, v250, 10
	v_readlane_b32 s19, v250, 11
	s_lshl_b32 s26, s7, 23
	s_lshr_b32 s27, s24, 2
	s_and_b32 s27, s27, 3
	s_lshl_b32 s27, s27, 8
	s_add_u32 s26, s26, s27
	s_lshl_b32 s27, s8, 6
	s_add_u32 s26, s26, s27
	s_add_u32 s18, s18, s26
	s_addc_u32 s19, s19, 0
	v_and_b32_e32 v92, 63, v216
	v_lshrrev_b32_e32 v93, 6, v216
	v_and_b32_e32 v94, 15, v216
	v_bfe_u32 v95, v216, 4, 2
	v_lshrrev_b32_e32 v132, 1, v93
	v_and_b32_e32 v133, 1, v93
	v_lshlrev_b32_e32 v8, 4, v216
	v_add_u32_e32 v9, 0x2000, v8
	v_lshlrev_b32_e32 v10, 12, v93
	v_lshl_add_u32 v10, v92, 3, v10
	s_lshl_b32 s26, s8, 10
	v_add_u32_e32 v10, s26, v10
	v_lshlrev_b32_e32 v11, 12, v132
	v_lshl_add_u32 v11, v133, 9, v11
	v_lshl_add_u32 v11, v92, 3, v11
	v_add_u32_e32 v11, s26, v11
	v_lshlrev_b32_e32 v12, 6, v93
	v_lshl_add_u32 v12, v95, 4, v12
	v_lshlrev_b32_e32 v134, 2, v132
	v_add_u32_e32 v134, v134, v95
	v_lshlrev_b32_e32 v13, 13, v134
	v_lshl_add_u32 v135, v133, 4, v94
	v_lshl_add_u32 v13, v135, 1, v13
	v_add_u32_e32 v14, 0x1000, v13
	v_lshrrev_b32_e32 v134, 4, v216
	v_mul_u32_u24_e32 v15, 0x110, v134
	v_lshl_add_u32 v15, v94, 4, v15
	v_mul_u32_u24_e32 v16, 0x110, v94
	v_lshl_add_u32 v134, v93, 2, v95
	v_lshl_add_u32 v16, v134, 3, v16
	v_add_u32_e32 v16, 0x4400, v16
	v_lshl_add_u32 v134, v132, 4, v94
	v_mul_u32_u24_e32 v17, 0x110, v134
	v_lshl_add_u32 v17, v95, 4, v17
	v_mul_u32_u24_e32 v18, 0x110, v135
	v_lshl_add_u32 v18, v95, 4, v18
	v_add_u32_e32 v18, 0x4400, v18
	v_mov_b32_e32 v0, 0
	v_mov_b32_e32 v1, 0
	v_mov_b32_e32 v2, 0
	v_mov_b32_e32 v3, 0
	v_mov_b32_e32 v4, 0
	v_mov_b32_e32 v5, 0
	v_mov_b32_e32 v6, 0
	v_mov_b32_e32 v7, 0
	global_load_dwordx4 v[20:23], v8, s[10:11]
	global_load_dwordx4 v[24:27], v9, s[10:11]
	global_load_dwordx2 v[28:29], v10, s[12:13]
	global_load_dwordx2 v[30:31], v10, s[12:13] offset:512
	global_load_dwordx2 v[32:33], v11, s[14:15]
	global_load_dwordx4 v[34:37], v12, s[16:17]
	s_add_u32 s10, s10, 0x4000
	s_addc_u32 s11, s11, 0
	s_add_u32 s12, s12, 0x8000
	s_addc_u32 s13, s13, 0
	s_add_u32 s14, s14, 0x4000
	s_addc_u32 s15, s15, 0
	s_add_u32 s16, s16, 0x200
	s_addc_u32 s17, s17, 0
	global_load_dwordx4 v[38:41], v8, s[10:11]
	global_load_dwordx4 v[42:45], v9, s[10:11]
	global_load_dwordx2 v[46:47], v10, s[12:13]
	global_load_dwordx2 v[48:49], v10, s[12:13] offset:512
	global_load_dwordx2 v[50:51], v11, s[14:15]
	global_load_dwordx4 v[52:55], v12, s[16:17]
	s_add_u32 s10, s10, 0x4000
	s_addc_u32 s11, s11, 0
	s_add_u32 s12, s12, 0x8000
	s_addc_u32 s13, s13, 0
	s_add_u32 s14, s14, 0x4000
	s_addc_u32 s15, s15, 0
	s_add_u32 s16, s16, 0x200
	s_addc_u32 s17, s17, 0
	global_load_dwordx4 v[56:59], v8, s[10:11]
	global_load_dwordx4 v[60:63], v9, s[10:11]
	global_load_dwordx2 v[64:65], v10, s[12:13]
	global_load_dwordx2 v[66:67], v10, s[12:13] offset:512
	global_load_dwordx2 v[68:69], v11, s[14:15]
	global_load_dwordx4 v[70:73], v12, s[16:17]
	s_add_u32 s10, s10, 0x4000
	s_addc_u32 s11, s11, 0
	s_add_u32 s12, s12, 0x8000
	s_addc_u32 s13, s13, 0
	s_add_u32 s14, s14, 0x4000
	s_addc_u32 s15, s15, 0
	s_add_u32 s16, s16, 0x200
	s_addc_u32 s17, s17, 0
	global_load_dwordx4 v[74:77], v8, s[10:11]
	global_load_dwordx4 v[78:81], v9, s[10:11]
	global_load_dwordx2 v[82:83], v10, s[12:13]
	global_load_dwordx2 v[84:85], v10, s[12:13] offset:512
	global_load_dwordx2 v[86:87], v11, s[14:15]
	global_load_dwordx4 v[88:91], v12, s[16:17]
	s_add_u32 s10, s10, 0x4000
	s_addc_u32 s11, s11, 0
	s_add_u32 s12, s12, 0x8000
	s_addc_u32 s13, s13, 0
	s_add_u32 s14, s14, 0x4000
	s_addc_u32 s15, s15, 0
	s_add_u32 s16, s16, 0x200
	s_addc_u32 s17, s17, 0
	s_mov_b32 s22, 0
	s_waitcnt vmcnt(18)
	ds_write_b128 v15, v[20:23] offset:0
	ds_write_b128 v15, v[24:27] offset:8704
	v_cvt_pk_bf16_f32 v132, v0, v1
	v_cvt_pk_bf16_f32 v133, v2, v3
	v_cvt_pk_bf16_f32 v134, v4, v5
	v_cvt_pk_bf16_f32 v135, v6, v7
	ds_write_b64 v16, v[132:133] offset:0
	ds_write_b64 v16, v[134:135] offset:4352
	v_lshlrev_b32_e32 v136, 16, v28
	v_and_b32_e32 v137, 0xffff0000, v28
	v_lshlrev_b32_e32 v138, 16, v29
	v_and_b32_e32 v139, 0xffff0000, v29
	v_lshlrev_b32_e32 v140, 16, v30
	v_and_b32_e32 v141, 0xffff0000, v30
	v_lshlrev_b32_e32 v142, 16, v31
	v_and_b32_e32 v143, 0xffff0000, v31
	v_pk_fma_f32 v[0:1], v[0:1], v[34:35], v[136:137]
	v_pk_fma_f32 v[2:3], v[2:3], v[36:37], v[138:139]
	v_pk_fma_f32 v[4:5], v[4:5], v[34:35], v[140:141]
	v_pk_fma_f32 v[6:7], v[6:7], v[36:37], v[142:143]
	s_waitcnt lgkmcnt(0)
	s_barrier
	ds_read_b128 v[96:99], v17 offset:0
	ds_read_b128 v[112:115], v18 offset:0
	ds_read_b128 v[100:103], v17 offset:64
	ds_read_b128 v[116:119], v18 offset:64
	ds_read_b128 v[104:107], v17 offset:128
	ds_read_b128 v[120:123], v18 offset:128
	ds_read_b128 v[108:111], v17 offset:192
	ds_read_b128 v[124:127], v18 offset:192
	v_lshlrev_b32_e32 v144, 16, v32
	v_and_b32_e32 v145, 0xffff0000, v32
	v_lshlrev_b32_e32 v146, 16, v33
	v_and_b32_e32 v147, 0xffff0000, v33
	s_waitcnt lgkmcnt(6)
	v_mfma_f32_16x16x32_bf16 v[128:131], v[96:99], v[112:115], 0
	s_waitcnt lgkmcnt(4)
	v_mfma_f32_16x16x32_bf16 v[128:131], v[100:103], v[116:119], v[128:131]
	s_waitcnt lgkmcnt(2)
	v_mfma_f32_16x16x32_bf16 v[128:131], v[104:107], v[120:123], v[128:131]
	s_waitcnt lgkmcnt(0)
	v_mfma_f32_16x16x32_bf16 v[128:131], v[108:111], v[124:127], v[128:131]
	s_nop 7
	s_nop 1
	v_add_f32_e32 v144, v128, v144
	v_add_f32_e32 v145, v129, v145
	v_add_f32_e32 v146, v130, v146
	v_add_f32_e32 v147, v131, v147
	v_cvt_pk_bf16_f32 v144, v144, s0
	v_cvt_pk_bf16_f32 v145, v145, s0
	v_cvt_pk_bf16_f32 v146, v146, s0
	v_cvt_pk_bf16_f32 v147, v147, s0
	global_store_short v13, v144, s[18:19]
	global_store_short v13, v145, s[18:19] offset:2048
	global_store_short v14, v146, s[18:19]
	global_store_short v14, v147, s[18:19] offset:2048
	global_load_dwordx4 v[20:23], v8, s[10:11]
	global_load_dwordx4 v[24:27], v9, s[10:11]
	global_load_dwordx2 v[28:29], v10, s[12:13]
	global_load_dwordx2 v[30:31], v10, s[12:13] offset:512
	global_load_dwordx2 v[32:33], v11, s[14:15]
	global_load_dwordx4 v[34:37], v12, s[16:17]
	s_add_u32 s18, s18, 0x20000
	s_addc_u32 s19, s19, 0
	s_cmp_lt_u32 s22, 59
	s_cbranch_scc0 .Ls2_na_p0
	s_add_u32 s10, s10, 0x4000
	s_addc_u32 s11, s11, 0
	s_add_u32 s12, s12, 0x8000
	s_addc_u32 s13, s13, 0
	s_add_u32 s14, s14, 0x4000
	s_addc_u32 s15, s15, 0
	s_add_u32 s16, s16, 0x200
	s_addc_u32 s17, s17, 0
.Ls2_na_p0:
	s_add_u32 s22, s22, 1
	s_waitcnt vmcnt(22)
	ds_write_b128 v15, v[38:41] offset:26112
	ds_write_b128 v15, v[42:45] offset:34816
	v_cvt_pk_bf16_f32 v132, v0, v1
	v_cvt_pk_bf16_f32 v133, v2, v3
	v_cvt_pk_bf16_f32 v134, v4, v5
	v_cvt_pk_bf16_f32 v135, v6, v7
	ds_write_b64 v16, v[132:133] offset:26112
	ds_write_b64 v16, v[134:135] offset:30464
	v_lshlrev_b32_e32 v136, 16, v46
	v_and_b32_e32 v137, 0xffff0000, v46
	v_lshlrev_b32_e32 v138, 16, v47
	v_and_b32_e32 v139, 0xffff0000, v47
	v_lshlrev_b32_e32 v140, 16, v48
	v_and_b32_e32 v141, 0xffff0000, v48
	v_lshlrev_b32_e32 v142, 16, v49
	v_and_b32_e32 v143, 0xffff0000, v49
	v_pk_fma_f32 v[0:1], v[0:1], v[52:53], v[136:137]
	v_pk_fma_f32 v[2:3], v[2:3], v[54:55], v[138:139]
	v_pk_fma_f32 v[4:5], v[4:5], v[52:53], v[140:141]
	v_pk_fma_f32 v[6:7], v[6:7], v[54:55], v[142:143]
	s_waitcnt lgkmcnt(0)
	s_barrier
	ds_read_b128 v[96:99], v17 offset:26112
	ds_read_b128 v[112:115], v18 offset:26112
	ds_read_b128 v[100:103], v17 offset:26176
	ds_read_b128 v[116:119], v18 offset:26176
	ds_read_b128 v[104:107], v17 offset:26240
	ds_read_b128 v[120:123], v18 offset:26240
	ds_read_b128 v[108:111], v17 offset:26304
	ds_read_b128 v[124:127], v18 offset:26304
	v_lshlrev_b32_e32 v144, 16, v50
	v_and_b32_e32 v145, 0xffff0000, v50
	v_lshlrev_b32_e32 v146, 16, v51
	v_and_b32_e32 v147, 0xffff0000, v51
	s_waitcnt lgkmcnt(6)
	v_mfma_f32_16x16x32_bf16 v[128:131], v[96:99], v[112:115], 0
	s_waitcnt lgkmcnt(4)
	v_mfma_f32_16x16x32_bf16 v[128:131], v[100:103], v[116:119], v[128:131]
	s_waitcnt lgkmcnt(2)
	v_mfma_f32_16x16x32_bf16 v[128:131], v[104:107], v[120:123], v[128:131]
	s_waitcnt lgkmcnt(0)
	v_mfma_f32_16x16x32_bf16 v[128:131], v[108:111], v[124:127], v[128:131]
	s_nop 7
	s_nop 1
	v_add_f32_e32 v144, v128, v144
	v_add_f32_e32 v145, v129, v145
	v_add_f32_e32 v146, v130, v146
	v_add_f32_e32 v147, v131, v147
	v_cvt_pk_bf16_f32 v144, v144, s0
	v_cvt_pk_bf16_f32 v145, v145, s0
	v_cvt_pk_bf16_f32 v146, v146, s0
	v_cvt_pk_bf16_f32 v147, v147, s0
	global_store_short v13, v144, s[18:19]
	global_store_short v13, v145, s[18:19] offset:2048
	global_store_short v14, v146, s[18:19]
	global_store_short v14, v147, s[18:19] offset:2048
	global_load_dwordx4 v[38:41], v8, s[10:11]
	global_load_dwordx4 v[42:45], v9, s[10:11]
	global_load_dwordx2 v[46:47], v10, s[12:13]
	global_load_dwordx2 v[48:49], v10, s[12:13] offset:512
	global_load_dwordx2 v[50:51], v11, s[14:15]
	global_load_dwordx4 v[52:55], v12, s[16:17]
	s_add_u32 s18, s18, 0x20000
	s_addc_u32 s19, s19, 0
	s_cmp_lt_u32 s22, 59
	s_cbranch_scc0 .Ls2_na_p1
	s_add_u32 s10, s10, 0x4000
	s_addc_u32 s11, s11, 0
	s_add_u32 s12, s12, 0x8000
	s_addc_u32 s13, s13, 0
	s_add_u32 s14, s14, 0x4000
	s_addc_u32 s15, s15, 0
	s_add_u32 s16, s16, 0x200
	s_addc_u32 s17, s17, 0
.Ls2_na_p1:
	s_add_u32 s22, s22, 1
	s_waitcnt vmcnt(26)
	ds_write_b128 v15, v[56:59] offset:0
	ds_write_b128 v15, v[60:63] offset:8704
	v_cvt_pk_bf16_f32 v132, v0, v1
	v_cvt_pk_bf16_f32 v133, v2, v3
	v_cvt_pk_bf16_f32 v134, v4, v5
	v_cvt_pk_bf16_f32 v135, v6, v7
	ds_write_b64 v16, v[132:133] offset:0
	ds_write_b64 v16, v[134:135] offset:4352
	v_lshlrev_b32_e32 v136, 16, v64
	v_and_b32_e32 v137, 0xffff0000, v64
	v_lshlrev_b32_e32 v138, 16, v65
	v_and_b32_e32 v139, 0xffff0000, v65
	v_lshlrev_b32_e32 v140, 16, v66
	v_and_b32_e32 v141, 0xffff0000, v66
	v_lshlrev_b32_e32 v142, 16, v67
	v_and_b32_e32 v143, 0xffff0000, v67
	v_pk_fma_f32 v[0:1], v[0:1], v[70:71], v[136:137]
	v_pk_fma_f32 v[2:3], v[2:3], v[72:73], v[138:139]
	v_pk_fma_f32 v[4:5], v[4:5], v[70:71], v[140:141]
	v_pk_fma_f32 v[6:7], v[6:7], v[72:73], v[142:143]
	s_waitcnt lgkmcnt(0)
	s_barrier
	ds_read_b128 v[96:99], v17 offset:0
	ds_read_b128 v[112:115], v18 offset:0
	ds_read_b128 v[100:103], v17 offset:64
	ds_read_b128 v[116:119], v18 offset:64
	ds_read_b128 v[104:107], v17 offset:128
	ds_read_b128 v[120:123], v18 offset:128
	ds_read_b128 v[108:111], v17 offset:192
	ds_read_b128 v[124:127], v18 offset:192
	v_lshlrev_b32_e32 v144, 16, v68
	v_and_b32_e32 v145, 0xffff0000, v68
	v_lshlrev_b32_e32 v146, 16, v69
	v_and_b32_e32 v147, 0xffff0000, v69
	s_waitcnt lgkmcnt(6)
	v_mfma_f32_16x16x32_bf16 v[128:131], v[96:99], v[112:115], 0
	s_waitcnt lgkmcnt(4)
	v_mfma_f32_16x16x32_bf16 v[128:131], v[100:103], v[116:119], v[128:131]
	s_waitcnt lgkmcnt(2)
	v_mfma_f32_16x16x32_bf16 v[128:131], v[104:107], v[120:123], v[128:131]
	s_waitcnt lgkmcnt(0)
	v_mfma_f32_16x16x32_bf16 v[128:131], v[108:111], v[124:127], v[128:131]
	s_nop 7
	s_nop 1
	v_add_f32_e32 v144, v128, v144
	v_add_f32_e32 v145, v129, v145
	v_add_f32_e32 v146, v130, v146
	v_add_f32_e32 v147, v131, v147
	v_cvt_pk_bf16_f32 v144, v144, s0
	v_cvt_pk_bf16_f32 v145, v145, s0
	v_cvt_pk_bf16_f32 v146, v146, s0
	v_cvt_pk_bf16_f32 v147, v147, s0
	global_store_short v13, v144, s[18:19]
	global_store_short v13, v145, s[18:19] offset:2048
	global_store_short v14, v146, s[18:19]
	global_store_short v14, v147, s[18:19] offset:2048
	global_load_dwordx4 v[56:59], v8, s[10:11]
	global_load_dwordx4 v[60:63], v9, s[10:11]
	global_load_dwordx2 v[64:65], v10, s[12:13]
	global_load_dwordx2 v[66:67], v10, s[12:13] offset:512
	global_load_dwordx2 v[68:69], v11, s[14:15]
	global_load_dwordx4 v[70:73], v12, s[16:17]
	s_add_u32 s18, s18, 0x20000
	s_addc_u32 s19, s19, 0
	s_cmp_lt_u32 s22, 59
	s_cbranch_scc0 .Ls2_na_p2
	s_add_u32 s10, s10, 0x4000
	s_addc_u32 s11, s11, 0
	s_add_u32 s12, s12, 0x8000
	s_addc_u32 s13, s13, 0
	s_add_u32 s14, s14, 0x4000
	s_addc_u32 s15, s15, 0
	s_add_u32 s16, s16, 0x200
	s_addc_u32 s17, s17, 0
.Ls2_na_p2:
	s_add_u32 s22, s22, 1
	s_waitcnt vmcnt(30)
	ds_write_b128 v15, v[74:77] offset:26112
	ds_write_b128 v15, v[78:81] offset:34816
	v_cvt_pk_bf16_f32 v132, v0, v1
	v_cvt_pk_bf16_f32 v133, v2, v3
	v_cvt_pk_bf16_f32 v134, v4, v5
	v_cvt_pk_bf16_f32 v135, v6, v7
	ds_write_b64 v16, v[132:133] offset:26112
	ds_write_b64 v16, v[134:135] offset:30464
	v_lshlrev_b32_e32 v136, 16, v82
	v_and_b32_e32 v137, 0xffff0000, v82
	v_lshlrev_b32_e32 v138, 16, v83
	v_and_b32_e32 v139, 0xffff0000, v83
	v_lshlrev_b32_e32 v140, 16, v84
	v_and_b32_e32 v141, 0xffff0000, v84
	v_lshlrev_b32_e32 v142, 16, v85
	v_and_b32_e32 v143, 0xffff0000, v85
	v_pk_fma_f32 v[0:1], v[0:1], v[88:89], v[136:137]
	v_pk_fma_f32 v[2:3], v[2:3], v[90:91], v[138:139]
	v_pk_fma_f32 v[4:5], v[4:5], v[88:89], v[140:141]
	v_pk_fma_f32 v[6:7], v[6:7], v[90:91], v[142:143]
	s_waitcnt lgkmcnt(0)
	s_barrier
	ds_read_b128 v[96:99], v17 offset:26112
	ds_read_b128 v[112:115], v18 offset:26112
	ds_read_b128 v[100:103], v17 offset:26176
	ds_read_b128 v[116:119], v18 offset:26176
	ds_read_b128 v[104:107], v17 offset:26240
	ds_read_b128 v[120:123], v18 offset:26240
	ds_read_b128 v[108:111], v17 offset:26304
	ds_read_b128 v[124:127], v18 offset:26304
	v_lshlrev_b32_e32 v144, 16, v86
	v_and_b32_e32 v145, 0xffff0000, v86
	v_lshlrev_b32_e32 v146, 16, v87
	v_and_b32_e32 v147, 0xffff0000, v87
	s_waitcnt lgkmcnt(6)
	v_mfma_f32_16x16x32_bf16 v[128:131], v[96:99], v[112:115], 0
	s_waitcnt lgkmcnt(4)
	v_mfma_f32_16x16x32_bf16 v[128:131], v[100:103], v[116:119], v[128:131]
	s_waitcnt lgkmcnt(2)
	v_mfma_f32_16x16x32_bf16 v[128:131], v[104:107], v[120:123], v[128:131]
	s_waitcnt lgkmcnt(0)
	v_mfma_f32_16x16x32_bf16 v[128:131], v[108:111], v[124:127], v[128:131]
	s_nop 7
	s_nop 1
	v_add_f32_e32 v144, v128, v144
	v_add_f32_e32 v145, v129, v145
	v_add_f32_e32 v146, v130, v146
	v_add_f32_e32 v147, v131, v147
	v_cvt_pk_bf16_f32 v144, v144, s0
	v_cvt_pk_bf16_f32 v145, v145, s0
	v_cvt_pk_bf16_f32 v146, v146, s0
	v_cvt_pk_bf16_f32 v147, v147, s0
	global_store_short v13, v144, s[18:19]
	global_store_short v13, v145, s[18:19] offset:2048
	global_store_short v14, v146, s[18:19]
	global_store_short v14, v147, s[18:19] offset:2048
	global_load_dwordx4 v[74:77], v8, s[10:11]
	global_load_dwordx4 v[78:81], v9, s[10:11]
	global_load_dwordx2 v[82:83], v10, s[12:13]
	global_load_dwordx2 v[84:85], v10, s[12:13] offset:512
	global_load_dwordx2 v[86:87], v11, s[14:15]
	global_load_dwordx4 v[88:91], v12, s[16:17]
	s_add_u32 s18, s18, 0x20000
	s_addc_u32 s19, s19, 0
	s_cmp_lt_u32 s22, 59
	s_cbranch_scc0 .Ls2_na_p3
	s_add_u32 s10, s10, 0x4000
	s_addc_u32 s11, s11, 0
	s_add_u32 s12, s12, 0x8000
	s_addc_u32 s13, s13, 0
	s_add_u32 s14, s14, 0x4000
	s_addc_u32 s15, s15, 0
	s_add_u32 s16, s16, 0x200
	s_addc_u32 s17, s17, 0
.Ls2_na_p3:
	s_add_u32 s22, s22, 1
.Ls2_loop:
	s_waitcnt vmcnt(30)
	ds_write_b128 v15, v[20:23] offset:0
	ds_write_b128 v15, v[24:27] offset:8704
	v_cvt_pk_bf16_f32 v132, v0, v1
	v_cvt_pk_bf16_f32 v133, v2, v3
	v_cvt_pk_bf16_f32 v134, v4, v5
	v_cvt_pk_bf16_f32 v135, v6, v7
	ds_write_b64 v16, v[132:133] offset:0
	ds_write_b64 v16, v[134:135] offset:4352
	v_lshlrev_b32_e32 v136, 16, v28
	v_and_b32_e32 v137, 0xffff0000, v28
	v_lshlrev_b32_e32 v138, 16, v29
	v_and_b32_e32 v139, 0xffff0000, v29
	v_lshlrev_b32_e32 v140, 16, v30
	v_and_b32_e32 v141, 0xffff0000, v30
	v_lshlrev_b32_e32 v142, 16, v31
	v_and_b32_e32 v143, 0xffff0000, v31
	v_pk_fma_f32 v[0:1], v[0:1], v[34:35], v[136:137]
	v_pk_fma_f32 v[2:3], v[2:3], v[36:37], v[138:139]
	v_pk_fma_f32 v[4:5], v[4:5], v[34:35], v[140:141]
	v_pk_fma_f32 v[6:7], v[6:7], v[36:37], v[142:143]
	s_waitcnt lgkmcnt(0)
	s_barrier
	ds_read_b128 v[96:99], v17 offset:0
	ds_read_b128 v[112:115], v18 offset:0
	ds_read_b128 v[100:103], v17 offset:64
	ds_read_b128 v[116:119], v18 offset:64
	ds_read_b128 v[104:107], v17 offset:128
	ds_read_b128 v[120:123], v18 offset:128
	ds_read_b128 v[108:111], v17 offset:192
	ds_read_b128 v[124:127], v18 offset:192
	v_lshlrev_b32_e32 v144, 16, v32
	v_and_b32_e32 v145, 0xffff0000, v32
	v_lshlrev_b32_e32 v146, 16, v33
	v_and_b32_e32 v147, 0xffff0000, v33
	s_waitcnt lgkmcnt(6)
	v_mfma_f32_16x16x32_bf16 v[128:131], v[96:99], v[112:115], 0
	s_waitcnt lgkmcnt(4)
	v_mfma_f32_16x16x32_bf16 v[128:131], v[100:103], v[116:119], v[128:131]
	s_waitcnt lgkmcnt(2)
	v_mfma_f32_16x16x32_bf16 v[128:131], v[104:107], v[120:123], v[128:131]
	s_waitcnt lgkmcnt(0)
	v_mfma_f32_16x16x32_bf16 v[128:131], v[108:111], v[124:127], v[128:131]
	s_nop 7
	s_nop 1
	v_add_f32_e32 v144, v128, v144
	v_add_f32_e32 v145, v129, v145
	v_add_f32_e32 v146, v130, v146
	v_add_f32_e32 v147, v131, v147
	v_cvt_pk_bf16_f32 v144, v144, s0
	v_cvt_pk_bf16_f32 v145, v145, s0
	v_cvt_pk_bf16_f32 v146, v146, s0
	v_cvt_pk_bf16_f32 v147, v147, s0
	global_store_short v13, v144, s[18:19]
	global_store_short v13, v145, s[18:19] offset:2048
	global_store_short v14, v146, s[18:19]
	global_store_short v14, v147, s[18:19] offset:2048
	global_load_dwordx4 v[20:23], v8, s[10:11]
	global_load_dwordx4 v[24:27], v9, s[10:11]
	global_load_dwordx2 v[28:29], v10, s[12:13]
	global_load_dwordx2 v[30:31], v10, s[12:13] offset:512
	global_load_dwordx2 v[32:33], v11, s[14:15]
	global_load_dwordx4 v[34:37], v12, s[16:17]
	s_add_u32 s18, s18, 0x20000
	s_addc_u32 s19, s19, 0
	s_cmp_lt_u32 s22, 59
	s_cbranch_scc0 .Ls2_na_l0
	s_add_u32 s10, s10, 0x4000
	s_addc_u32 s11, s11, 0
	s_add_u32 s12, s12, 0x8000
	s_addc_u32 s13, s13, 0
	s_add_u32 s14, s14, 0x4000
	s_addc_u32 s15, s15, 0
	s_add_u32 s16, s16, 0x200
	s_addc_u32 s17, s17, 0
.Ls2_na_l0:
	s_add_u32 s22, s22, 1
	s_waitcnt vmcnt(30)
	ds_write_b128 v15, v[38:41] offset:26112
	ds_write_b128 v15, v[42:45] offset:34816
	v_cvt_pk_bf16_f32 v132, v0, v1
	v_cvt_pk_bf16_f32 v133, v2, v3
	v_cvt_pk_bf16_f32 v134, v4, v5
	v_cvt_pk_bf16_f32 v135, v6, v7
	ds_write_b64 v16, v[132:133] offset:26112
	ds_write_b64 v16, v[134:135] offset:30464
	v_lshlrev_b32_e32 v136, 16, v46
	v_and_b32_e32 v137, 0xffff0000, v46
	v_lshlrev_b32_e32 v138, 16, v47
	v_and_b32_e32 v139, 0xffff0000, v47
	v_lshlrev_b32_e32 v140, 16, v48
	v_and_b32_e32 v141, 0xffff0000, v48
	v_lshlrev_b32_e32 v142, 16, v49
	v_and_b32_e32 v143, 0xffff0000, v49
	v_pk_fma_f32 v[0:1], v[0:1], v[52:53], v[136:137]
	v_pk_fma_f32 v[2:3], v[2:3], v[54:55], v[138:139]
	v_pk_fma_f32 v[4:5], v[4:5], v[52:53], v[140:141]
	v_pk_fma_f32 v[6:7], v[6:7], v[54:55], v[142:143]
	s_waitcnt lgkmcnt(0)
	s_barrier
	ds_read_b128 v[96:99], v17 offset:26112
	ds_read_b128 v[112:115], v18 offset:26112
	ds_read_b128 v[100:103], v17 offset:26176
	ds_read_b128 v[116:119], v18 offset:26176
	ds_read_b128 v[104:107], v17 offset:26240
	ds_read_b128 v[120:123], v18 offset:26240
	ds_read_b128 v[108:111], v17 offset:26304
	ds_read_b128 v[124:127], v18 offset:26304
	v_lshlrev_b32_e32 v144, 16, v50
	v_and_b32_e32 v145, 0xffff0000, v50
	v_lshlrev_b32_e32 v146, 16, v51
	v_and_b32_e32 v147, 0xffff0000, v51
	s_waitcnt lgkmcnt(6)
	v_mfma_f32_16x16x32_bf16 v[128:131], v[96:99], v[112:115], 0
	s_waitcnt lgkmcnt(4)
	v_mfma_f32_16x16x32_bf16 v[128:131], v[100:103], v[116:119], v[128:131]
	s_waitcnt lgkmcnt(2)
	v_mfma_f32_16x16x32_bf16 v[128:131], v[104:107], v[120:123], v[128:131]
	s_waitcnt lgkmcnt(0)
	v_mfma_f32_16x16x32_bf16 v[128:131], v[108:111], v[124:127], v[128:131]
	s_nop 7
	s_nop 1
	v_add_f32_e32 v144, v128, v144
	v_add_f32_e32 v145, v129, v145
	v_add_f32_e32 v146, v130, v146
	v_add_f32_e32 v147, v131, v147
	v_cvt_pk_bf16_f32 v144, v144, s0
	v_cvt_pk_bf16_f32 v145, v145, s0
	v_cvt_pk_bf16_f32 v146, v146, s0
	v_cvt_pk_bf16_f32 v147, v147, s0
	global_store_short v13, v144, s[18:19]
	global_store_short v13, v145, s[18:19] offset:2048
	global_store_short v14, v146, s[18:19]
	global_store_short v14, v147, s[18:19] offset:2048
	global_load_dwordx4 v[38:41], v8, s[10:11]
	global_load_dwordx4 v[42:45], v9, s[10:11]
	global_load_dwordx2 v[46:47], v10, s[12:13]
	global_load_dwordx2 v[48:49], v10, s[12:13] offset:512
	global_load_dwordx2 v[50:51], v11, s[14:15]
	global_load_dwordx4 v[52:55], v12, s[16:17]
	s_add_u32 s18, s18, 0x20000
	s_addc_u32 s19, s19, 0
	s_cmp_lt_u32 s22, 59
	s_cbranch_scc0 .Ls2_na_l1
	s_add_u32 s10, s10, 0x4000
	s_addc_u32 s11, s11, 0
	s_add_u32 s12, s12, 0x8000
	s_addc_u32 s13, s13, 0
	s_add_u32 s14, s14, 0x4000
	s_addc_u32 s15, s15, 0
	s_add_u32 s16, s16, 0x200
	s_addc_u32 s17, s17, 0
.Ls2_na_l1:
	s_add_u32 s22, s22, 1
	s_waitcnt vmcnt(30)
	ds_write_b128 v15, v[56:59] offset:0
	ds_write_b128 v15, v[60:63] offset:8704
	v_cvt_pk_bf16_f32 v132, v0, v1
	v_cvt_pk_bf16_f32 v133, v2, v3
	v_cvt_pk_bf16_f32 v134, v4, v5
	v_cvt_pk_bf16_f32 v135, v6, v7
	ds_write_b64 v16, v[132:133] offset:0
	ds_write_b64 v16, v[134:135] offset:4352
	v_lshlrev_b32_e32 v136, 16, v64
	v_and_b32_e32 v137, 0xffff0000, v64
	v_lshlrev_b32_e32 v138, 16, v65
	v_and_b32_e32 v139, 0xffff0000, v65
	v_lshlrev_b32_e32 v140, 16, v66
	v_and_b32_e32 v141, 0xffff0000, v66
	v_lshlrev_b32_e32 v142, 16, v67
	v_and_b32_e32 v143, 0xffff0000, v67
	v_pk_fma_f32 v[0:1], v[0:1], v[70:71], v[136:137]
	v_pk_fma_f32 v[2:3], v[2:3], v[72:73], v[138:139]
	v_pk_fma_f32 v[4:5], v[4:5], v[70:71], v[140:141]
	v_pk_fma_f32 v[6:7], v[6:7], v[72:73], v[142:143]
	s_waitcnt lgkmcnt(0)
	s_barrier
	ds_read_b128 v[96:99], v17 offset:0
	ds_read_b128 v[112:115], v18 offset:0
	ds_read_b128 v[100:103], v17 offset:64
	ds_read_b128 v[116:119], v18 offset:64
	ds_read_b128 v[104:107], v17 offset:128
	ds_read_b128 v[120:123], v18 offset:128
	ds_read_b128 v[108:111], v17 offset:192
	ds_read_b128 v[124:127], v18 offset:192
	v_lshlrev_b32_e32 v144, 16, v68
	v_and_b32_e32 v145, 0xffff0000, v68
	v_lshlrev_b32_e32 v146, 16, v69
	v_and_b32_e32 v147, 0xffff0000, v69
	s_waitcnt lgkmcnt(6)
	v_mfma_f32_16x16x32_bf16 v[128:131], v[96:99], v[112:115], 0
	s_waitcnt lgkmcnt(4)
	v_mfma_f32_16x16x32_bf16 v[128:131], v[100:103], v[116:119], v[128:131]
	s_waitcnt lgkmcnt(2)
	v_mfma_f32_16x16x32_bf16 v[128:131], v[104:107], v[120:123], v[128:131]
	s_waitcnt lgkmcnt(0)
	v_mfma_f32_16x16x32_bf16 v[128:131], v[108:111], v[124:127], v[128:131]
	s_nop 7
	s_nop 1
	v_add_f32_e32 v144, v128, v144
	v_add_f32_e32 v145, v129, v145
	v_add_f32_e32 v146, v130, v146
	v_add_f32_e32 v147, v131, v147
	v_cvt_pk_bf16_f32 v144, v144, s0
	v_cvt_pk_bf16_f32 v145, v145, s0
	v_cvt_pk_bf16_f32 v146, v146, s0
	v_cvt_pk_bf16_f32 v147, v147, s0
	global_store_short v13, v144, s[18:19]
	global_store_short v13, v145, s[18:19] offset:2048
	global_store_short v14, v146, s[18:19]
	global_store_short v14, v147, s[18:19] offset:2048
	global_load_dwordx4 v[56:59], v8, s[10:11]
	global_load_dwordx4 v[60:63], v9, s[10:11]
	global_load_dwordx2 v[64:65], v10, s[12:13]
	global_load_dwordx2 v[66:67], v10, s[12:13] offset:512
	global_load_dwordx2 v[68:69], v11, s[14:15]
	global_load_dwordx4 v[70:73], v12, s[16:17]
	s_add_u32 s18, s18, 0x20000
	s_addc_u32 s19, s19, 0
	s_cmp_lt_u32 s22, 59
	s_cbranch_scc0 .Ls2_na_l2
	s_add_u32 s10, s10, 0x4000
	s_addc_u32 s11, s11, 0
	s_add_u32 s12, s12, 0x8000
	s_addc_u32 s13, s13, 0
	s_add_u32 s14, s14, 0x4000
	s_addc_u32 s15, s15, 0
	s_add_u32 s16, s16, 0x200
	s_addc_u32 s17, s17, 0

.Ls2_na_l3:
	s_add_u32 s22, s22, 1
	s_cmp_lt_u32 s22, 64
	s_cbranch_scc1 .Ls2_loop
	s_waitcnt vmcnt(0)
	s_branch .LBB0_549
